# seams 2-9: the XCD leader's acquire-side invalidate moved from behind its arrival (in front of its arrival polls) to beside its L2 writeback; the other workgroups keep it behind their arrival; on top
# speedup vs baseline: 1.0043x; 1.0006x over previous
; __device__ __forceinline__ unsigned xb_ld(unsigned* p)              { return __hip_atomic_load(p, __ATOMIC_RELAXED, __HIP_MEMORY_SCOPE_AGENT); }
; __device__ __forceinline__ unsigned xb_add(unsigned* p, unsigned v) { return __hip_atomic_fetch_add(p, v, __ATOMIC_RELAXED, __HIP_MEMORY_SCOPE_AGENT); }
; #define XB_SPIN(cond, bar) do { unsigned _sp = 0; while (cond) { __builtin_amdgcn_s_sleep(1); \
;     if ((++_sp & 255u) == 0u) { if (xb_ld(&(bar)[XB_TMO])) break; if (_sp > XB_SPIN_CAP) { atomicAdd(&(bar)[XB_TMO], 1u); break; } } } } while (0)
; __device__ __forceinline__ void xcd_barrier(const XcdBarrier& b, const int wid) {
;     ...
;             __builtin_amdgcn_fence(__ATOMIC_RELEASE, "agent");
;             asm volatile("s_waitcnt vmcnt(0)" ::: "memory");
;             const unsigned og = xb_add(&bar[XB_TOP], 1u);
;             const unsigned tg = og / nx;
;             if (og + 1u == (tg + 1u) * nx) xb_add(&bar[XB_TOPGEN], 1u);
;             else XB_SPIN(xb_ld(&bar[XB_TOPGEN]) == tg, bar);
;             __builtin_amdgcn_fence(__ATOMIC_ACQUIRE, "agent");
;             xb_add(&bar[XB_XGEN(b.x)], 1u);
.Lxb2_go:
	buffer_wbl2 sc1
	buffer_inv sc1
	s_waitcnt vmcnt(0)
	v_mov_b32_e32 v6, 0x7000
	v_mov_b32_e32 v7, 1
	global_atomic_add v6, v7, s[86:87] offset:1024
	s_branch .Lxb2_w0
.Lxb2_wait:
	buffer_inv sc1
.Lxb2_w0:
	v_mov_b32_e32 v0, 0

; __device__ __forceinline__ unsigned xb_ld(unsigned* p)              { return __hip_atomic_load(p, __ATOMIC_RELAXED, __HIP_MEMORY_SCOPE_AGENT); }
; #define XB_SPIN(cond, bar) do { unsigned _sp = 0; while (cond) { __builtin_amdgcn_s_sleep(1); \
;     if ((++_sp & 255u) == 0u) { if (xb_ld(&(bar)[XB_TMO])) break; if (_sp > XB_SPIN_CAP) { atomicAdd(&(bar)[XB_TMO], 1u); break; } } } } while (0)
; __device__ __forceinline__ void xcd_barrier(const XcdBarrier& b, const int wid) {
;     ...
;             XB_SPIN(xb_ld(&bar[XB_XGEN(b.x)]) == gen, bar);
;             __builtin_amdgcn_fence(__ATOMIC_ACQUIRE, "agent");
;             asm volatile("s_waitcnt vmcnt(0)" ::: "memory");
.Lxb3_wait:
	buffer_inv sc1
.Lxb3_w0:
	v_mov_b32_e32 v0, 0

; __device__ __forceinline__ unsigned xb_ld(unsigned* p)              { return __hip_atomic_load(p, __ATOMIC_RELAXED, __HIP_MEMORY_SCOPE_AGENT); }
; #define XB_SPIN(cond, bar) do { unsigned _sp = 0; while (cond) { __builtin_amdgcn_s_sleep(1); \
;     if ((++_sp & 255u) == 0u) { if (xb_ld(&(bar)[XB_TMO])) break; if (_sp > XB_SPIN_CAP) { atomicAdd(&(bar)[XB_TMO], 1u); break; } } } } while (0)
; __device__ __forceinline__ void xcd_barrier(const XcdBarrier& b, const int wid) {
;     ...
;             XB_SPIN(xb_ld(&bar[XB_XGEN(b.x)]) == gen, bar);
;             __builtin_amdgcn_fence(__ATOMIC_ACQUIRE, "agent");
;             asm volatile("s_waitcnt vmcnt(0)" ::: "memory");
.Lxb4_wait:
	buffer_inv sc1
.Lxb4_w0:
	v_mov_b32_e32 v0, 0

; __device__ __forceinline__ unsigned xb_ld(unsigned* p)              { return __hip_atomic_load(p, __ATOMIC_RELAXED, __HIP_MEMORY_SCOPE_AGENT); }
; #define XB_SPIN(cond, bar) do { unsigned _sp = 0; while (cond) { __builtin_amdgcn_s_sleep(1); \
;     if ((++_sp & 255u) == 0u) { if (xb_ld(&(bar)[XB_TMO])) break; if (_sp > XB_SPIN_CAP) { atomicAdd(&(bar)[XB_TMO], 1u); break; } } } } while (0)
; __device__ __forceinline__ void xcd_barrier(const XcdBarrier& b, const int wid) {
;     ...
;             XB_SPIN(xb_ld(&bar[XB_XGEN(b.x)]) == gen, bar);
;             __builtin_amdgcn_fence(__ATOMIC_ACQUIRE, "agent");
;             asm volatile("s_waitcnt vmcnt(0)" ::: "memory");
.Lxb5_wait:
	buffer_inv sc1
.Lxb5_w0:
	v_mov_b32_e32 v0, 0

; __device__ __forceinline__ unsigned xb_ld(unsigned* p)              { return __hip_atomic_load(p, __ATOMIC_RELAXED, __HIP_MEMORY_SCOPE_AGENT); }
; #define XB_SPIN(cond, bar) do { unsigned _sp = 0; while (cond) { __builtin_amdgcn_s_sleep(1); \
;     if ((++_sp & 255u) == 0u) { if (xb_ld(&(bar)[XB_TMO])) break; if (_sp > XB_SPIN_CAP) { atomicAdd(&(bar)[XB_TMO], 1u); break; } } } } while (0)
; __device__ __forceinline__ void xcd_barrier(const XcdBarrier& b, const int wid) {
;     ...
;             XB_SPIN(xb_ld(&bar[XB_XGEN(b.x)]) == gen, bar);
;             __builtin_amdgcn_fence(__ATOMIC_ACQUIRE, "agent");
;             asm volatile("s_waitcnt vmcnt(0)" ::: "memory");
.Lxb6_wait:
	buffer_inv sc1
.Lxb6_w0:
	v_mov_b32_e32 v0, 0

; __device__ __forceinline__ unsigned xb_ld(unsigned* p)              { return __hip_atomic_load(p, __ATOMIC_RELAXED, __HIP_MEMORY_SCOPE_AGENT); }
; #define XB_SPIN(cond, bar) do { unsigned _sp = 0; while (cond) { __builtin_amdgcn_s_sleep(1); \
;     if ((++_sp & 255u) == 0u) { if (xb_ld(&(bar)[XB_TMO])) break; if (_sp > XB_SPIN_CAP) { atomicAdd(&(bar)[XB_TMO], 1u); break; } } } } while (0)
; __device__ __forceinline__ void xcd_barrier(const XcdBarrier& b, const int wid) {
;     ...
;             XB_SPIN(xb_ld(&bar[XB_XGEN(b.x)]) == gen, bar);
;             __builtin_amdgcn_fence(__ATOMIC_ACQUIRE, "agent");
;             asm volatile("s_waitcnt vmcnt(0)" ::: "memory");
.Lxb7_wait:
	buffer_inv sc1
.Lxb7_w0:
	v_mov_b32_e32 v0, 0

; __device__ __forceinline__ unsigned xb_ld(unsigned* p)              { return __hip_atomic_load(p, __ATOMIC_RELAXED, __HIP_MEMORY_SCOPE_AGENT); }
; #define XB_SPIN(cond, bar) do { unsigned _sp = 0; while (cond) { __builtin_amdgcn_s_sleep(1); \
;     if ((++_sp & 255u) == 0u) { if (xb_ld(&(bar)[XB_TMO])) break; if (_sp > XB_SPIN_CAP) { atomicAdd(&(bar)[XB_TMO], 1u); break; } } } } while (0)
; __device__ __forceinline__ void xcd_barrier(const XcdBarrier& b, const int wid) {
;     ...
;             XB_SPIN(xb_ld(&bar[XB_XGEN(b.x)]) == gen, bar);
;             __builtin_amdgcn_fence(__ATOMIC_ACQUIRE, "agent");
;             asm volatile("s_waitcnt vmcnt(0)" ::: "memory");
.Lxb8_wait:
	buffer_inv sc1
.Lxb8_w0:
	v_mov_b32_e32 v0, 0

; __device__ __forceinline__ unsigned xb_ld(unsigned* p)              { return __hip_atomic_load(p, __ATOMIC_RELAXED, __HIP_MEMORY_SCOPE_AGENT); }
; #define XB_SPIN(cond, bar) do { unsigned _sp = 0; while (cond) { __builtin_amdgcn_s_sleep(1); \
;     if ((++_sp & 255u) == 0u) { if (xb_ld(&(bar)[XB_TMO])) break; if (_sp > XB_SPIN_CAP) { atomicAdd(&(bar)[XB_TMO], 1u); break; } } } } while (0)
; __device__ __forceinline__ void xcd_barrier(const XcdBarrier& b, const int wid) {
;     ...
;             XB_SPIN(xb_ld(&bar[XB_XGEN(b.x)]) == gen, bar);
;             __builtin_amdgcn_fence(__ATOMIC_ACQUIRE, "agent");
;             asm volatile("s_waitcnt vmcnt(0)" ::: "memory");
.Lxb9_wait:
	buffer_inv sc1
.Lxb9_w0:
	v_mov_b32_e32 v0, 0
